# GEMM K-loop: LDS-DMA pieces balanced 4/4/4/4 across the four load segments (last two pieces of phases 2/4 issued right after the closing barrier), waits 8/6/8/6
# speedup vs baseline: 1.0051x; 1.0004x over previous
; #define PG8_STAGE(bufoff, gbase, voff) do { _Pragma("unroll") for (int _i = 0; _i < 2; ++_i) \
;         __builtin_amdgcn_global_load_lds((const unsigned*)((const char*)(gbase) + (voff)[_i]), (PG8_LAS unsigned*)(lds + (bufoff) + ldsw + _i * 8192), 16, 0, 0); } while (0)
; #define PG8_LDA(dst, b, h) do { _Pragma("unroll") for (int m = 0; m < 4; ++m) _Pragma("unroll") for (int k = 0; k < 2; ++k) dst[m][k] = *(const PG8_LAS bf16x8*)(lds + PG8_SA(b, h) + aoff + m * 2048 + k * 1024); } while (0)
; #define PG8_LDB(dst, b, h) do { _Pragma("unroll") for (int n = 0; n < 2; ++n) _Pragma("unroll") for (int k = 0; k < 2; ++k) dst[n][k] = *(const PG8_LAS bf16x8*)(lds + PG8_SB(b, h) + boff + n * 2048 + k * 1024); } while (0)
; #define PG8_MMA(ai, bj, At, Bt) do { __builtin_amdgcn_s_setprio(1); _Pragma("unroll") for (int m = 0; m < 4; ++m) _Pragma("unroll") for (int n = 0; n < 2; ++n) _Pragma("unroll") for (int k = 0; k < 2; ++k) \
;         acc[ai][bj][m][n] = __builtin_amdgcn_mfma_f32_16x16x32_bf16(Bt[n][k], At[m][k], acc[ai][bj][m][n], 0, 0, 0); __builtin_amdgcn_s_setprio(0); } while (0)
; #define PG8_WAIT_V(n) asm volatile("s_waitcnt vmcnt(" #n ")" ::: "memory")
; #define PG8_WAIT_L(n) asm volatile("s_waitcnt lgkmcnt(" #n ")" ::: "memory")
; #define PG8_BAR __builtin_amdgcn_s_barrier()
; #define PG8_SCHED __builtin_amdgcn_sched_barrier(0)
; template <class Epi, class Sched, bool ALIGN_EPI = false, bool SP2 = false>
; __device__ __forceinline__ void gemm_phase(PG8_LAS unsigned char* lds, const Gemm g, const Sched& S, const Epi& E) {
;     ...
;             PG8_LDB(B0, 0, 0); PG8_LDB(B1, 0, 1); PG8_SCHED; PG8_LDA(At, 0, 0); PG8_STAGE(PG8_SA(1, 1), a1 + hstep, voffA);
;             PG8_WAIT_V(8); PG8_WAIT_L(0); PG8_BAR; PG8_MMA(0, 0, At, B0); PG8_MMA(0, 1, At, B1); PG8_BAR; PG8_SCHED;
;             PG8_LDA(At, 0, 1); PG8_STAGE(PG8_SB(0, 0), b2, voffB); PG8_STAGE(PG8_SB(0, 1), b2 + hstep, voffB); PG8_STAGE(PG8_SA(0, 0), a2, voffA);
;             PG8_WAIT_V(8); PG8_WAIT_L(0); PG8_BAR; PG8_MMA(1, 0, At, B0); PG8_MMA(1, 1, At, B1); PG8_BAR; PG8_SCHED;
.LBB0_410:
	s_add_i32 vcc_hi, s28, 2
	s_add_u32 s86, s14, 0x80
	s_addc_u32 s29, s15, 0
	s_add_i32 s88, 0, 0x10000
	s_cmp_eq_u32 s83, s28
	s_cselect_b32 s29, s30, s29
	s_cselect_b32 s28, s31, s86
	s_cselect_b32 s87, s37, vcc_lo
	s_cselect_b32 s86, s45, s47
	s_add_i32 s89, 0, 0x14000
	v_add_u32_e32 v86, s88, v161
	v_add_u32_e32 v172, s89, v161
	ds_read_b128 v[74:77], v86
	ds_read_b128 v[78:81], v86 offset:1024
	ds_read_b128 v[82:85], v86 offset:2048
	ds_read_b128 v[86:89], v86 offset:3072
	ds_read_b128 v[156:159], v172
	ds_read_b128 v[164:167], v172 offset:1024
	ds_read_b128 v[168:171], v172 offset:2048
	ds_read_b128 v[172:175], v172 offset:3072
	v_lshl_add_u64 v[204:205], s[14:15], 0, v[152:153]
	s_add_i32 m0, s61, 0xc000
	ds_read_b128 v[176:179], v163
	ds_read_b128 v[180:183], v163 offset:1024
	ds_read_b128 v[184:187], v163 offset:2048
	ds_read_b128 v[188:191], v163 offset:3072
	ds_read_b128 v[192:195], v163 offset:4096
	ds_read_b128 v[196:199], v163 offset:5120
	ds_read_b128 v[200:203], v163 offset:6144
	ds_read_b128 v[210:213], v163 offset:7168
	global_load_lds_dwordx4 v[204:205], off
	v_lshl_add_u64 v[204:205], s[14:15], 0, v[154:155]
	s_add_i32 m0, s61, 0xe000
	s_nop 0
	global_load_lds_dwordx4 v[204:205], off
	s_waitcnt vmcnt(8)
	s_waitcnt lgkmcnt(0)
	s_barrier
	s_setprio 1
	s_waitcnt lgkmcnt(0)
	v_mfma_f32_16x16x32_bf16 v[142:145], v[74:77], v[176:179], v[142:145]
	v_mfma_f32_16x16x32_bf16 v[138:141], v[82:85], v[176:179], v[138:141]
	v_mfma_f32_16x16x32_bf16 v[126:129], v[74:77], v[184:187], v[126:129]
	v_mfma_f32_16x16x32_bf16 v[122:125], v[82:85], v[184:187], v[122:125]
	v_mfma_f32_16x16x32_bf16 v[110:113], v[74:77], v[192:195], v[110:113]
	v_mfma_f32_16x16x32_bf16 v[106:109], v[82:85], v[192:195], v[106:109]
	v_mfma_f32_16x16x32_bf16 v[94:97], v[74:77], v[200:203], v[94:97]
	v_mfma_f32_16x16x32_bf16 v[90:93], v[82:85], v[200:203], v[90:93]
	v_mfma_f32_16x16x32_bf16 v[142:145], v[78:81], v[180:183], v[142:145]
	v_mfma_f32_16x16x32_bf16 v[138:141], v[86:89], v[180:183], v[138:141]
	v_mfma_f32_16x16x32_bf16 v[126:129], v[78:81], v[188:191], v[126:129]
	v_mfma_f32_16x16x32_bf16 v[122:125], v[86:89], v[188:191], v[122:125]
	v_mfma_f32_16x16x32_bf16 v[110:113], v[78:81], v[196:199], v[110:113]
	v_mfma_f32_16x16x32_bf16 v[106:109], v[86:89], v[196:199], v[106:109]
	v_mfma_f32_16x16x32_bf16 v[94:97], v[78:81], v[210:213], v[94:97]
	v_mfma_f32_16x16x32_bf16 v[90:93], v[86:89], v[210:213], v[90:93]
	s_setprio 0
	s_setprio 1
	v_mfma_f32_16x16x32_bf16 v[134:137], v[156:159], v[176:179], v[134:137]
	v_mfma_f32_16x16x32_bf16 v[130:133], v[168:171], v[176:179], v[130:133]
	v_mfma_f32_16x16x32_bf16 v[118:121], v[156:159], v[184:187], v[118:121]
	v_mfma_f32_16x16x32_bf16 v[114:117], v[168:171], v[184:187], v[114:117]
	v_mfma_f32_16x16x32_bf16 v[102:105], v[156:159], v[192:195], v[102:105]
	v_mfma_f32_16x16x32_bf16 v[98:101], v[168:171], v[192:195], v[98:101]
	v_mfma_f32_16x16x32_bf16 v[70:73], v[156:159], v[200:203], v[70:73]
	v_mfma_f32_16x16x32_bf16 v[66:69], v[168:171], v[200:203], v[66:69]
	v_mfma_f32_16x16x32_bf16 v[134:137], v[164:167], v[180:183], v[134:137]
	v_mfma_f32_16x16x32_bf16 v[130:133], v[172:175], v[180:183], v[130:133]
	v_mfma_f32_16x16x32_bf16 v[118:121], v[164:167], v[188:191], v[118:121]
	v_mfma_f32_16x16x32_bf16 v[114:117], v[172:175], v[188:191], v[114:117]
	v_mfma_f32_16x16x32_bf16 v[102:105], v[164:167], v[196:199], v[102:105]
	v_mfma_f32_16x16x32_bf16 v[98:101], v[172:175], v[196:199], v[98:101]
	v_mfma_f32_16x16x32_bf16 v[70:73], v[164:167], v[210:213], v[70:73]
	v_mfma_f32_16x16x32_bf16 v[66:69], v[172:175], v[210:213], v[66:69]
	s_setprio 0
	s_barrier
	s_add_i32 s88, s88, s62
	v_lshl_add_u64 v[204:205], s[86:87], 0, v[0:1]
	s_mov_b32 m0, s88
	ds_read_b128 v[176:179], v163 offset:16384
	ds_read_b128 v[180:183], v163 offset:17408
	ds_read_b128 v[184:187], v163 offset:18432
	ds_read_b128 v[188:191], v163 offset:19456
	ds_read_b128 v[192:195], v163 offset:20480
	ds_read_b128 v[196:199], v163 offset:21504
	ds_read_b128 v[200:203], v163 offset:22528
	ds_read_b128 v[210:213], v163 offset:23552
	global_load_lds_dwordx4 v[204:205], off
	s_add_i32 m0, s88, 0x2000
	v_lshl_add_u64 v[226:227], s[86:87], 0, v[150:151]
	s_add_u32 s86, s86, s10
	s_addc_u32 s87, s87, 0
	s_add_i32 s88, s89, s62
	global_load_lds_dwordx4 v[226:227], off
	v_lshl_add_u64 v[228:229], s[86:87], 0, v[0:1]
	s_mov_b32 m0, s88
	v_lshl_add_u64 v[230:231], s[86:87], 0, v[150:151]
	global_load_lds_dwordx4 v[228:229], off
	s_add_i32 m0, s88, 0x2000
	v_lshl_add_u64 v[232:233], s[28:29], 0, v[146:147]
	global_load_lds_dwordx4 v[230:231], off
	v_lshl_add_u64 v[234:235], s[28:29], 0, v[148:149]
	s_waitcnt vmcnt(6)
	s_waitcnt lgkmcnt(0)
	s_barrier
; #define PG8_STAGE(bufoff, gbase, voff) do { _Pragma("unroll") for (int _i = 0; _i < 2; ++_i) \
;         __builtin_amdgcn_global_load_lds((const unsigned*)((const char*)(gbase) + (voff)[_i]), (PG8_LAS unsigned*)(lds + (bufoff) + ldsw + _i * 8192), 16, 0, 0); } while (0)
; #define PG8_LDA(dst, b, h) do { _Pragma("unroll") for (int m = 0; m < 4; ++m) _Pragma("unroll") for (int k = 0; k < 2; ++k) dst[m][k] = *(const PG8_LAS bf16x8*)(lds + PG8_SA(b, h) + aoff + m * 2048 + k * 1024); } while (0)
; #define PG8_LDB(dst, b, h) do { _Pragma("unroll") for (int n = 0; n < 2; ++n) _Pragma("unroll") for (int k = 0; k < 2; ++k) dst[n][k] = *(const PG8_LAS bf16x8*)(lds + PG8_SB(b, h) + boff + n * 2048 + k * 1024); } while (0)
; #define PG8_MMA(ai, bj, At, Bt) do { __builtin_amdgcn_s_setprio(1); _Pragma("unroll") for (int m = 0; m < 4; ++m) _Pragma("unroll") for (int n = 0; n < 2; ++n) _Pragma("unroll") for (int k = 0; k < 2; ++k) \
;         acc[ai][bj][m][n] = __builtin_amdgcn_mfma_f32_16x16x32_bf16(Bt[n][k], At[m][k], acc[ai][bj][m][n], 0, 0, 0); __builtin_amdgcn_s_setprio(0); } while (0)
; #define PG8_WAIT_V(n) asm volatile("s_waitcnt vmcnt(" #n ")" ::: "memory")
; #define PG8_WAIT_L(n) asm volatile("s_waitcnt lgkmcnt(" #n ")" ::: "memory")
; #define PG8_BAR __builtin_amdgcn_s_barrier()
; #define PG8_SCHED __builtin_amdgcn_sched_barrier(0)
; template <class Epi, class Sched, bool ALIGN_EPI = false, bool SP2 = false>
; __device__ __forceinline__ void gemm_phase(PG8_LAS unsigned char* lds, const Gemm g, const Sched& S, const Epi& E) {
;     ...
;             PG8_WAIT_V(8); PG8_WAIT_L(0); PG8_BAR; PG8_MMA(1, 0, At, B0); PG8_MMA(1, 1, At, B1); PG8_BAR; PG8_SCHED;
;             PG8_LDB(B0, 1, 0); PG8_LDB(B1, 1, 1); PG8_SCHED; PG8_LDA(At, 1, 0); PG8_STAGE(PG8_SA(0, 1), a2 + hstep, voffA);
;             PG8_WAIT_V(8); PG8_WAIT_L(0); PG8_BAR; PG8_MMA(0, 0, At, B0); PG8_MMA(0, 1, At, B1); PG8_BAR; PG8_SCHED;
	s_setprio 1
	s_waitcnt lgkmcnt(0)
	v_mfma_f32_16x16x32_bf16 v[62:65], v[74:77], v[176:179], v[62:65]
	v_mfma_f32_16x16x32_bf16 v[58:61], v[82:85], v[176:179], v[58:61]
	v_mfma_f32_16x16x32_bf16 v[46:49], v[74:77], v[184:187], v[46:49]
	v_mfma_f32_16x16x32_bf16 v[42:45], v[82:85], v[184:187], v[42:45]
	v_mfma_f32_16x16x32_bf16 v[30:33], v[74:77], v[192:195], v[30:33]
	v_mfma_f32_16x16x32_bf16 v[26:29], v[82:85], v[192:195], v[26:29]
	v_mfma_f32_16x16x32_bf16 v[14:17], v[74:77], v[200:203], v[14:17]
	v_mfma_f32_16x16x32_bf16 v[10:13], v[82:85], v[200:203], v[10:13]
	v_mfma_f32_16x16x32_bf16 v[62:65], v[78:81], v[180:183], v[62:65]
	v_mfma_f32_16x16x32_bf16 v[58:61], v[86:89], v[180:183], v[58:61]
	v_mfma_f32_16x16x32_bf16 v[46:49], v[78:81], v[188:191], v[46:49]
	v_mfma_f32_16x16x32_bf16 v[42:45], v[86:89], v[188:191], v[42:45]
	v_mfma_f32_16x16x32_bf16 v[30:33], v[78:81], v[196:199], v[30:33]
	v_mfma_f32_16x16x32_bf16 v[26:29], v[86:89], v[196:199], v[26:29]
	v_mfma_f32_16x16x32_bf16 v[14:17], v[78:81], v[210:213], v[14:17]
	v_mfma_f32_16x16x32_bf16 v[10:13], v[86:89], v[210:213], v[10:13]
	s_setprio 0
	s_setprio 1
	v_mfma_f32_16x16x32_bf16 v[54:57], v[156:159], v[176:179], v[54:57]
	v_mfma_f32_16x16x32_bf16 v[50:53], v[168:171], v[176:179], v[50:53]
	v_mfma_f32_16x16x32_bf16 v[38:41], v[156:159], v[184:187], v[38:41]
	v_mfma_f32_16x16x32_bf16 v[34:37], v[168:171], v[184:187], v[34:37]
	v_mfma_f32_16x16x32_bf16 v[22:25], v[156:159], v[192:195], v[22:25]
	v_mfma_f32_16x16x32_bf16 v[18:21], v[168:171], v[192:195], v[18:21]
	v_mfma_f32_16x16x32_bf16 v[6:9], v[156:159], v[200:203], v[6:9]
	v_mfma_f32_16x16x32_bf16 v[2:5], v[168:171], v[200:203], v[2:5]
	v_mfma_f32_16x16x32_bf16 v[54:57], v[164:167], v[180:183], v[54:57]
	v_mfma_f32_16x16x32_bf16 v[50:53], v[172:175], v[180:183], v[50:53]
	v_mfma_f32_16x16x32_bf16 v[38:41], v[164:167], v[188:191], v[38:41]
	v_mfma_f32_16x16x32_bf16 v[34:37], v[172:175], v[188:191], v[34:37]
	v_mfma_f32_16x16x32_bf16 v[22:25], v[164:167], v[196:199], v[22:25]
	v_mfma_f32_16x16x32_bf16 v[18:21], v[172:175], v[196:199], v[18:21]
	v_mfma_f32_16x16x32_bf16 v[6:9], v[164:167], v[210:213], v[6:9]
	v_mfma_f32_16x16x32_bf16 v[2:5], v[172:175], v[210:213], v[2:5]
	s_setprio 0
	s_barrier
	s_mov_b32 m0, s61
	s_nop 0
	global_load_lds_dwordx4 v[232:233], off
	s_mov_b32 m0, s77
	s_nop 0
	global_load_lds_dwordx4 v[234:235], off
	s_add_i32 s86, 0, 0x18000
	s_add_i32 s87, 0, 0x1c000
	v_add_u32_e32 v86, s86, v161
	v_add_u32_e32 v172, s87, v161
	ds_read_b128 v[74:77], v86
	ds_read_b128 v[78:81], v86 offset:1024
	ds_read_b128 v[82:85], v86 offset:2048
	ds_read_b128 v[86:89], v86 offset:3072
	ds_read_b128 v[156:159], v172
	ds_read_b128 v[164:167], v172 offset:1024
	ds_read_b128 v[168:171], v172 offset:2048
	ds_read_b128 v[172:175], v172 offset:3072
	s_add_u32 s28, s28, s10
	s_addc_u32 s29, s29, 0
	s_mov_b32 m0, s78
	v_lshl_add_u64 v[236:237], s[28:29], 0, v[146:147]
	ds_read_b128 v[176:179], v163 offset:32768
	ds_read_b128 v[180:183], v163 offset:33792
	ds_read_b128 v[184:187], v163 offset:34816
	ds_read_b128 v[188:191], v163 offset:35840
	ds_read_b128 v[192:195], v163 offset:36864
	ds_read_b128 v[196:199], v163 offset:37888
	ds_read_b128 v[200:203], v163 offset:38912
	ds_read_b128 v[210:213], v163 offset:39936
	global_load_lds_dwordx4 v[236:237], off
	v_lshl_add_u64 v[236:237], s[28:29], 0, v[148:149]
	s_mov_b32 m0, s79
	s_nop 0
	global_load_lds_dwordx4 v[236:237], off
	s_waitcnt vmcnt(8)
	s_waitcnt lgkmcnt(0)
	s_barrier
	s_setprio 1
	s_waitcnt lgkmcnt(0)
	v_mfma_f32_16x16x32_bf16 v[142:145], v[74:77], v[176:179], v[142:145]
	v_mfma_f32_16x16x32_bf16 v[138:141], v[82:85], v[176:179], v[138:141]
	v_mfma_f32_16x16x32_bf16 v[126:129], v[74:77], v[184:187], v[126:129]
	v_mfma_f32_16x16x32_bf16 v[122:125], v[82:85], v[184:187], v[122:125]
	v_mfma_f32_16x16x32_bf16 v[110:113], v[74:77], v[192:195], v[110:113]
	v_mfma_f32_16x16x32_bf16 v[106:109], v[82:85], v[192:195], v[106:109]
	v_mfma_f32_16x16x32_bf16 v[94:97], v[74:77], v[200:203], v[94:97]
	v_mfma_f32_16x16x32_bf16 v[90:93], v[82:85], v[200:203], v[90:93]
	v_mfma_f32_16x16x32_bf16 v[142:145], v[78:81], v[180:183], v[142:145]
	v_mfma_f32_16x16x32_bf16 v[138:141], v[86:89], v[180:183], v[138:141]
	v_mfma_f32_16x16x32_bf16 v[126:129], v[78:81], v[188:191], v[126:129]
	v_mfma_f32_16x16x32_bf16 v[122:125], v[86:89], v[188:191], v[122:125]
	v_mfma_f32_16x16x32_bf16 v[110:113], v[78:81], v[196:199], v[110:113]
	v_mfma_f32_16x16x32_bf16 v[106:109], v[86:89], v[196:199], v[106:109]
	v_mfma_f32_16x16x32_bf16 v[94:97], v[78:81], v[210:213], v[94:97]
	v_mfma_f32_16x16x32_bf16 v[90:93], v[86:89], v[210:213], v[90:93]
	s_setprio 0
	s_setprio 1
	v_mfma_f32_16x16x32_bf16 v[134:137], v[156:159], v[176:179], v[134:137]
	v_mfma_f32_16x16x32_bf16 v[130:133], v[168:171], v[176:179], v[130:133]
	v_mfma_f32_16x16x32_bf16 v[118:121], v[156:159], v[184:187], v[118:121]
	v_mfma_f32_16x16x32_bf16 v[114:117], v[168:171], v[184:187], v[114:117]
	v_mfma_f32_16x16x32_bf16 v[102:105], v[156:159], v[192:195], v[102:105]
	v_mfma_f32_16x16x32_bf16 v[98:101], v[168:171], v[192:195], v[98:101]
	v_mfma_f32_16x16x32_bf16 v[70:73], v[156:159], v[200:203], v[70:73]
	v_mfma_f32_16x16x32_bf16 v[66:69], v[168:171], v[200:203], v[66:69]
	v_mfma_f32_16x16x32_bf16 v[134:137], v[164:167], v[180:183], v[134:137]
	v_mfma_f32_16x16x32_bf16 v[130:133], v[172:175], v[180:183], v[130:133]
	v_mfma_f32_16x16x32_bf16 v[118:121], v[164:167], v[188:191], v[118:121]
	v_mfma_f32_16x16x32_bf16 v[114:117], v[172:175], v[188:191], v[114:117]
	v_mfma_f32_16x16x32_bf16 v[102:105], v[164:167], v[196:199], v[102:105]
	v_mfma_f32_16x16x32_bf16 v[98:101], v[172:175], v[196:199], v[98:101]
	v_mfma_f32_16x16x32_bf16 v[70:73], v[164:167], v[210:213], v[70:73]
	v_mfma_f32_16x16x32_bf16 v[66:69], v[172:175], v[210:213], v[66:69]
	s_setprio 0
	s_barrier
; #define PG8_STAGE(bufoff, gbase, voff) do { _Pragma("unroll") for (int _i = 0; _i < 2; ++_i) \
;         __builtin_amdgcn_global_load_lds((const unsigned*)((const char*)(gbase) + (voff)[_i]), (PG8_LAS unsigned*)(lds + (bufoff) + ldsw + _i * 8192), 16, 0, 0); } while (0)
; #define PG8_LDA(dst, b, h) do { _Pragma("unroll") for (int m = 0; m < 4; ++m) _Pragma("unroll") for (int k = 0; k < 2; ++k) dst[m][k] = *(const PG8_LAS bf16x8*)(lds + PG8_SA(b, h) + aoff + m * 2048 + k * 1024); } while (0)
; #define PG8_MMA(ai, bj, At, Bt) do { __builtin_amdgcn_s_setprio(1); _Pragma("unroll") for (int m = 0; m < 4; ++m) _Pragma("unroll") for (int n = 0; n < 2; ++n) _Pragma("unroll") for (int k = 0; k < 2; ++k) \
;         acc[ai][bj][m][n] = __builtin_amdgcn_mfma_f32_16x16x32_bf16(Bt[n][k], At[m][k], acc[ai][bj][m][n], 0, 0, 0); __builtin_amdgcn_s_setprio(0); } while (0)
; #define PG8_WAIT_V(n) asm volatile("s_waitcnt vmcnt(" #n ")" ::: "memory")
; #define PG8_WAIT_L(n) asm volatile("s_waitcnt lgkmcnt(" #n ")" ::: "memory")
; #define PG8_BAR __builtin_amdgcn_s_barrier()
; #define PG8_SCHED __builtin_amdgcn_sched_barrier(0)
; template <class Epi, class Sched, bool ALIGN_EPI = false, bool SP2 = false>
; __device__ __forceinline__ void gemm_phase(PG8_LAS unsigned char* lds, const Gemm g, const Sched& S, const Epi& E) {
;     ...
;         for (int t = 0; t < nt; t += 2) {
;     ...
;             PG8_LDA(At, 1, 1); PG8_STAGE(PG8_SB(1, 0), b3, voffB); PG8_STAGE(PG8_SB(1, 1), b3 + hstep, voffB); PG8_STAGE(PG8_SA(1, 0), a3, voffA);
;             PG8_WAIT_V(8); PG8_WAIT_L(0); PG8_BAR; PG8_MMA(1, 0, At, B0); PG8_MMA(1, 1, At, B1); PG8_BAR; PG8_SCHED;
	s_add_i32 s28, s86, s62
	v_lshl_add_u64 v[204:205], v[204:205], 0, s[24:25]
	s_mov_b32 m0, s28
	ds_read_b128 v[176:179], v163 offset:49152
	ds_read_b128 v[180:183], v163 offset:50176
	ds_read_b128 v[184:187], v163 offset:51200
	ds_read_b128 v[188:191], v163 offset:52224
	ds_read_b128 v[192:195], v163 offset:53248
	ds_read_b128 v[196:199], v163 offset:54272
	ds_read_b128 v[200:203], v163 offset:55296
	ds_read_b128 v[210:213], v163 offset:56320
	global_load_lds_dwordx4 v[204:205], off
	v_lshl_add_u64 v[204:205], v[226:227], 0, s[24:25]
	s_add_i32 m0, s28, 0x2000
	s_add_i32 s28, s87, s62
	global_load_lds_dwordx4 v[204:205], off
	v_lshl_add_u64 v[204:205], v[228:229], 0, s[24:25]
	s_mov_b32 m0, s28
	s_nop 0
	global_load_lds_dwordx4 v[204:205], off
	v_lshl_add_u64 v[204:205], v[230:231], 0, s[24:25]
	s_add_i32 m0, s28, 0x2000
	s_nop 0
	global_load_lds_dwordx4 v[204:205], off
	s_waitcnt vmcnt(6)
	s_waitcnt lgkmcnt(0)
	s_barrier
	s_setprio 1
	s_waitcnt lgkmcnt(0)
	v_mfma_f32_16x16x32_bf16 v[62:65], v[74:77], v[176:179], v[62:65]
	v_mfma_f32_16x16x32_bf16 v[58:61], v[82:85], v[176:179], v[58:61]
	v_mfma_f32_16x16x32_bf16 v[46:49], v[74:77], v[184:187], v[46:49]
	v_mfma_f32_16x16x32_bf16 v[42:45], v[82:85], v[184:187], v[42:45]
	v_mfma_f32_16x16x32_bf16 v[30:33], v[74:77], v[192:195], v[30:33]
	v_mfma_f32_16x16x32_bf16 v[26:29], v[82:85], v[192:195], v[26:29]
	v_mfma_f32_16x16x32_bf16 v[14:17], v[74:77], v[200:203], v[14:17]
	v_mfma_f32_16x16x32_bf16 v[10:13], v[82:85], v[200:203], v[10:13]
	v_mfma_f32_16x16x32_bf16 v[62:65], v[78:81], v[180:183], v[62:65]
	v_mfma_f32_16x16x32_bf16 v[58:61], v[86:89], v[180:183], v[58:61]
	v_mfma_f32_16x16x32_bf16 v[46:49], v[78:81], v[188:191], v[46:49]
	v_mfma_f32_16x16x32_bf16 v[42:45], v[86:89], v[188:191], v[42:45]
	v_mfma_f32_16x16x32_bf16 v[30:33], v[78:81], v[196:199], v[30:33]
	v_mfma_f32_16x16x32_bf16 v[26:29], v[86:89], v[196:199], v[26:29]
	v_mfma_f32_16x16x32_bf16 v[14:17], v[78:81], v[210:213], v[14:17]
	v_mfma_f32_16x16x32_bf16 v[10:13], v[86:89], v[210:213], v[10:13]
	s_setprio 0
	s_setprio 1
	v_mfma_f32_16x16x32_bf16 v[54:57], v[156:159], v[176:179], v[54:57]
	v_mfma_f32_16x16x32_bf16 v[50:53], v[168:171], v[176:179], v[50:53]
	v_mfma_f32_16x16x32_bf16 v[38:41], v[156:159], v[184:187], v[38:41]
	v_mfma_f32_16x16x32_bf16 v[34:37], v[168:171], v[184:187], v[34:37]
	v_mfma_f32_16x16x32_bf16 v[22:25], v[156:159], v[192:195], v[22:25]
	v_mfma_f32_16x16x32_bf16 v[18:21], v[168:171], v[192:195], v[18:21]
	v_mfma_f32_16x16x32_bf16 v[6:9], v[156:159], v[200:203], v[6:9]
	v_mfma_f32_16x16x32_bf16 v[2:5], v[168:171], v[200:203], v[2:5]
	v_mfma_f32_16x16x32_bf16 v[54:57], v[164:167], v[180:183], v[54:57]
	v_mfma_f32_16x16x32_bf16 v[50:53], v[172:175], v[180:183], v[50:53]
	v_mfma_f32_16x16x32_bf16 v[38:41], v[164:167], v[188:191], v[38:41]
	v_mfma_f32_16x16x32_bf16 v[34:37], v[172:175], v[188:191], v[34:37]
	v_mfma_f32_16x16x32_bf16 v[22:25], v[164:167], v[196:199], v[22:25]
	v_mfma_f32_16x16x32_bf16 v[18:21], v[172:175], v[196:199], v[18:21]
	v_mfma_f32_16x16x32_bf16 v[6:9], v[164:167], v[210:213], v[6:9]
	v_mfma_f32_16x16x32_bf16 v[2:5], v[172:175], v[210:213], v[2:5]
	s_setprio 0
	s_barrier
	v_lshl_add_u64 v[204:205], v[232:233], 0, s[24:25]
	s_mov_b32 m0, s80
	s_nop 0
	global_load_lds_dwordx4 v[204:205], off
	v_lshl_add_u64 v[204:205], v[234:235], 0, s[24:25]
	s_mov_b32 m0, s81
	s_nop 0
	global_load_lds_dwordx4 v[204:205], off
	s_add_u32 s14, s14, 0x100
	s_addc_u32 s15, s15, 0
	s_add_u32 s47, s47, 0x100
	s_addc_u32 vcc_lo, vcc_lo, 0
	s_cmp_ge_u32 vcc_hi, s82
	s_mov_b32 s28, vcc_hi
	s_cbranch_scc0 .LBB0_410
	s_and_b64 vcc, exec, s[34:35]
	s_cbranch_vccz .LBB0_413
	s_barrier
